# seam: one designated workgroup per XCD (blockIdx < 8) starts an early L2 write-back from its idle wave 1 at seam entry; leader write-back unchanged
# baseline (speedup 1.0000x reference)
; __device__ __forceinline__ unsigned xb_ld(unsigned* p)              { return __hip_atomic_load(p, __ATOMIC_RELAXED, __HIP_MEMORY_SCOPE_AGENT); }
; __device__ __forceinline__ unsigned xb_add(unsigned* p, unsigned v) { return __hip_atomic_fetch_add(p, v, __ATOMIC_RELAXED, __HIP_MEMORY_SCOPE_AGENT); }
; #define XB_SPIN(cond, bar) do { unsigned _sp = 0; while (cond) { __builtin_amdgcn_s_sleep(1); \
;     if ((++_sp & 255u) == 0u) { if (xb_ld(&(bar)[XB_TMO])) break; if (_sp > XB_SPIN_CAP) { atomicAdd(&(bar)[XB_TMO], 1u); break; } } } } while (0)
; __device__ __forceinline__ void xcd_barrier(const XcdBarrier& b) {
;     asm volatile("s_waitcnt vmcnt(0)" ::: "memory");
;     __syncthreads();
;     if (threadIdx.x == 0) {
;         unsigned* bar = b.bar;
;         __builtin_amdgcn_s_waitcnt(0);
;         unsigned nloc = b.st[0], nx = b.st[1];
;         if (nloc == 0u) { xcd_barrier_complete(bar, b.x, nloc, nx); b.st[0] = nloc; b.st[1] = nx; }
;         const unsigned old = xb_add(&bar[XB_XSUB(b.x)], 1u);
;         const unsigned gen = old / nloc;
;         if (old + 1u == (gen + 1u) * nloc) {
;             __builtin_amdgcn_fence(__ATOMIC_RELEASE, "agent");
;             asm volatile("s_waitcnt vmcnt(0)" ::: "memory");
;             const unsigned og = xb_add(&bar[XB_TOP], 1u);
;             const unsigned tg = og / nx;
;             if (og + 1u == (tg + 1u) * nx) xb_add(&bar[XB_TOPGEN], 1u);
;             else XB_SPIN(xb_ld(&bar[XB_TOPGEN]) == tg, bar);
;             __builtin_amdgcn_fence(__ATOMIC_ACQUIRE, "agent");
;             xb_add(&bar[XB_XGEN(b.x)], 1u);
;             asm volatile("s_waitcnt vmcnt(0)" ::: "memory");
;         } else {
;             XB_SPIN(xb_ld(&bar[XB_XGEN(b.x)]) == gen, bar);
;             __builtin_amdgcn_fence(__ATOMIC_ACQUIRE, "agent");
;             asm volatile("s_waitcnt vmcnt(0)" ::: "memory");
;         }
.Lseam_inv_0:
	v_readfirstlane_b32 s98, v1
	s_nop 0
	s_lshr_b32 s98, s98, 6
	s_cmp_lg_u32 s98, 1
	s_cbranch_scc1 .Lseam_cv_0
	s_mov_b64 exec, -1
	s_cmp_ge_u32 s87, 8
	s_cbranch_scc1 .Lseam_nowb_0
	buffer_wbl2 sc1
.Lseam_nowb_0:
	buffer_inv sc1
	s_waitcnt vmcnt(0)
	s_branch .LBB0_339

; __device__ __forceinline__ unsigned xb_ld(unsigned* p)              { return __hip_atomic_load(p, __ATOMIC_RELAXED, __HIP_MEMORY_SCOPE_AGENT); }
; __device__ __forceinline__ unsigned xb_add(unsigned* p, unsigned v) { return __hip_atomic_fetch_add(p, v, __ATOMIC_RELAXED, __HIP_MEMORY_SCOPE_AGENT); }
; #define XB_SPIN(cond, bar) do { unsigned _sp = 0; while (cond) { __builtin_amdgcn_s_sleep(1); \
;     if ((++_sp & 255u) == 0u) { if (xb_ld(&(bar)[XB_TMO])) break; if (_sp > XB_SPIN_CAP) { atomicAdd(&(bar)[XB_TMO], 1u); break; } } } } while (0)
; __device__ __forceinline__ void xcd_barrier(const XcdBarrier& b) {
;     asm volatile("s_waitcnt vmcnt(0)" ::: "memory");
;     __syncthreads();
;     if (threadIdx.x == 0) {
;         unsigned* bar = b.bar;
;         __builtin_amdgcn_s_waitcnt(0);
;         unsigned nloc = b.st[0], nx = b.st[1];
;         if (nloc == 0u) { xcd_barrier_complete(bar, b.x, nloc, nx); b.st[0] = nloc; b.st[1] = nx; }
;         const unsigned old = xb_add(&bar[XB_XSUB(b.x)], 1u);
;         const unsigned gen = old / nloc;
;         if (old + 1u == (gen + 1u) * nloc) {
;             __builtin_amdgcn_fence(__ATOMIC_RELEASE, "agent");
;             asm volatile("s_waitcnt vmcnt(0)" ::: "memory");
;             const unsigned og = xb_add(&bar[XB_TOP], 1u);
;             const unsigned tg = og / nx;
;             if (og + 1u == (tg + 1u) * nx) xb_add(&bar[XB_TOPGEN], 1u);
;             else XB_SPIN(xb_ld(&bar[XB_TOPGEN]) == tg, bar);
;             __builtin_amdgcn_fence(__ATOMIC_ACQUIRE, "agent");
;             xb_add(&bar[XB_XGEN(b.x)], 1u);
;             asm volatile("s_waitcnt vmcnt(0)" ::: "memory");
;         } else {
;             XB_SPIN(xb_ld(&bar[XB_XGEN(b.x)]) == gen, bar);
;             __builtin_amdgcn_fence(__ATOMIC_ACQUIRE, "agent");
;             asm volatile("s_waitcnt vmcnt(0)" ::: "memory");
;         }
.Lseam_nowb_4:
	buffer_inv sc1
	s_waitcnt vmcnt(0)
